# P5b: next item's conv operand rows touched (L1/L2 prefetch) right after each item's first barrier; on top of output-group queue + barrier invalidate move
# speedup vs baseline: 1.0004x; 1.0004x over previous
.LBB0_848:
	s_or_b64 exec, exec, s[60:61]
	global_load_dwordx4 v[26:29], v[128:129], off offset:16
	global_load_dwordx4 v[30:33], v[128:129], off
	global_load_dwordx4 v[58:61], v[142:143], off offset:16
	global_load_dwordx4 v[90:93], v[142:143], off
	global_load_dwordx4 v[42:45], v[128:129], off offset:2064
	global_load_dwordx4 v[66:69], v[128:129], off offset:2048
	global_load_dwordx4 v[62:65], v[142:143], off offset:2064
	global_load_dwordx4 v[94:97], v[142:143], off offset:2048
	global_load_dwordx4 v[50:53], v[130:131], off offset:16
	global_load_dwordx4 v[86:89], v[130:131], off
	global_load_dwordx4 v[46:49], v[132:133], off offset:16
	global_load_dwordx4 v[78:81], v[132:133], off
	v_lshl_add_u64 v[10:11], s[26:27], 0, v[146:147]
	v_lshl_add_u64 v[12:13], v[10:11], 0, s[36:37]
	v_add_co_u32_e32 v10, vcc, 0xb000000, v10
	s_waitcnt vmcnt(13)
	v_lshlrev_b32_e32 v178, 16, v119
	v_addc_co_u32_e32 v11, vcc, 0, v11, vcc
	global_load_dwordx4 v[70:73], v[134:135], off
	global_load_dwordx4 v[168:171], v[10:11], off
	global_load_dwordx4 v[172:175], v[12:13], off offset:16
	global_load_dwordx4 v[82:85], v[134:135], off offset:16
	global_load_dwordx4 v[74:77], v[136:137], off
	global_load_dwordx4 v[54:57], v[136:137], off offset:16
	global_load_dwordx4 v[22:25], v[138:139], off offset:16
	global_load_dwordx4 v[34:37], v[138:139], off
	global_load_dwordx4 v[10:13], v[140:141], off offset:16
	global_load_dwordx4 v[18:21], v[140:141], off
	v_and_b32_e32 v179, 0xffff0000, v119
	v_lshlrev_b32_e32 v180, 16, v120
	v_and_b32_e32 v181, 0xffff0000, v120
	v_lshlrev_b32_e32 v182, 16, v121
	v_and_b32_e32 v183, 0xffff0000, v121
	s_waitcnt vmcnt(22)
	v_lshlrev_b32_e32 v184, 16, v102
	v_and_b32_e32 v185, 0xffff0000, v102
	v_lshlrev_b32_e32 v186, 16, v103
	v_and_b32_e32 v187, 0xffff0000, v103
	v_lshlrev_b32_e32 v188, 16, v104
	v_and_b32_e32 v189, 0xffff0000, v104
	v_lshlrev_b32_e32 v190, 16, v105
	v_and_b32_e32 v191, 0xffff0000, v105
	v_lshlrev_b32_e32 v102, 16, v114
	v_and_b32_e32 v103, 0xffff0000, v114
	v_lshlrev_b32_e32 v104, 16, v115
	v_and_b32_e32 v105, 0xffff0000, v115
	v_lshlrev_b32_e32 v114, 16, v116
	v_and_b32_e32 v115, 0xffff0000, v116
	v_lshlrev_b32_e32 v176, 16, v118
	v_and_b32_e32 v177, 0xffff0000, v118
	v_lshlrev_b32_e32 v116, 16, v117
	v_and_b32_e32 v117, 0xffff0000, v117
	v_lshlrev_b32_e32 v118, 16, v38
	v_and_b32_e32 v119, 0xffff0000, v38
	v_lshlrev_b32_e32 v38, 16, v39
	v_and_b32_e32 v39, 0xffff0000, v39
	v_lshlrev_b32_e32 v154, 16, v106
	v_and_b32_e32 v155, 0xffff0000, v106
	v_lshlrev_b32_e32 v106, 16, v107
	v_and_b32_e32 v107, 0xffff0000, v107
	v_lshlrev_b32_e32 v120, 16, v40
	v_and_b32_e32 v121, 0xffff0000, v40
	v_lshlrev_b32_e32 v40, 16, v41
	v_and_b32_e32 v41, 0xffff0000, v41
	v_lshlrev_b32_e32 v194, 16, v14
	v_and_b32_e32 v195, 0xffff0000, v14
	v_lshlrev_b32_e32 v196, 16, v15
	v_and_b32_e32 v197, 0xffff0000, v15
	v_lshlrev_b32_e32 v198, 16, v16
	v_and_b32_e32 v199, 0xffff0000, v16
	v_lshlrev_b32_e32 v200, 16, v17
	v_and_b32_e32 v201, 0xffff0000, v17
	v_lshlrev_b32_e32 v192, 16, v112
	v_and_b32_e32 v193, 0xffff0000, v112
	v_lshlrev_b32_e32 v112, 16, v113
	v_and_b32_e32 v113, 0xffff0000, v113
	v_lshl_add_u64 v[146:147], v[146:147], 0, s[42:43]
	v_lshl_add_u64 v[148:149], v[148:149], 0, s[58:59]
	v_lshl_add_u64 v[150:151], v[150:151], 0, s[34:35]
	s_waitcnt vmcnt(8)
	ds_write_b128 v159, v[168:171] offset:17408
	s_waitcnt vmcnt(7)
	ds_write_b128 v159, v[172:175] offset:17424
	v_pk_fma_f32 v[178:179], v[32:33], v[178:179], v[92:93]
	v_pk_fma_f32 v[180:181], v[26:27], v[180:181], v[58:59]
	v_pk_fma_f32 v[182:183], v[28:29], v[182:183], v[60:61]
	v_pk_fma_f32 v[184:185], v[66:67], v[184:185], v[94:95]
	v_pk_fma_f32 v[186:187], v[68:69], v[186:187], v[96:97]
	v_pk_fma_f32 v[178:179], v[88:89], v[104:105], v[178:179]
	v_pk_fma_f32 v[180:181], v[50:51], v[114:115], v[180:181]
	v_lshlrev_b32_e32 v170, 16, v108
	v_and_b32_e32 v171, 0xffff0000, v108
	v_pk_fma_f32 v[176:177], v[30:31], v[176:177], v[90:91]
	v_pk_fma_f32 v[188:189], v[42:43], v[188:189], v[62:63]
	v_pk_fma_f32 v[190:191], v[44:45], v[190:191], v[64:65]
	v_pk_fma_f32 v[182:183], v[52:53], v[116:117], v[182:183]
	v_pk_fma_f32 v[186:187], v[80:81], v[38:39], v[186:187]
	v_pk_fma_f32 v[184:185], v[78:79], v[118:119], v[184:185]
	v_pk_fma_f32 v[168:169], v[72:73], v[106:107], v[178:179]
	v_lshlrev_b32_e32 v108, 16, v109
	v_and_b32_e32 v109, 0xffff0000, v109
	s_waitcnt vmcnt(6)
	v_pk_fma_f32 v[172:173], v[82:83], v[170:171], v[180:181]
	v_lshlrev_b32_e32 v178, 16, v98
	v_and_b32_e32 v179, 0xffff0000, v98
	v_lshlrev_b32_e32 v180, 16, v99
	v_and_b32_e32 v181, 0xffff0000, v99
	v_pk_fma_f32 v[176:177], v[86:87], v[102:103], v[176:177]
	v_pk_fma_f32 v[190:191], v[48:49], v[40:41], v[190:191]
	v_pk_fma_f32 v[188:189], v[46:47], v[120:121], v[188:189]
	v_pk_fma_f32 v[174:175], v[84:85], v[108:109], v[182:183]
	s_waitcnt vmcnt(5)
	v_pk_fma_f32 v[98:99], v[74:75], v[178:179], v[184:185]
	v_pk_fma_f32 v[182:183], v[76:77], v[180:181], v[186:187]
	v_lshlrev_b32_e32 v184, 16, v100
	v_and_b32_e32 v185, 0xffff0000, v100
	v_lshlrev_b32_e32 v186, 16, v101
	v_and_b32_e32 v187, 0xffff0000, v101
	v_pk_fma_f32 v[176:177], v[70:71], v[154:155], v[176:177]
	s_waitcnt vmcnt(4)
	v_pk_fma_f32 v[100:101], v[54:55], v[184:185], v[188:189]
	v_pk_fma_f32 v[188:189], v[56:57], v[186:187], v[190:191]
	v_lshlrev_b32_e32 v190, 16, v110
	v_and_b32_e32 v191, 0xffff0000, v110
	s_waitcnt vmcnt(2)
	v_pk_fma_f32 v[176:177], v[34:35], v[190:191], v[176:177]
	v_lshlrev_b32_e32 v110, 16, v111
	v_mul_f32_e32 v14, 0xbfb8aa3b, v176
	v_mul_f32_e32 v15, 0xbfb8aa3b, v177
	v_exp_f32_e32 v14, v14
	v_exp_f32_e32 v15, v15
	v_and_b32_e32 v111, 0xffff0000, v111
	v_pk_fma_f32 v[168:169], v[36:37], v[110:111], v[168:169]
	v_add_f32_e32 v14, 1.0, v14
	v_add_f32_e32 v15, 1.0, v15
	v_rcp_f32_e32 v14, v14
	v_rcp_f32_e32 v15, v15
	v_mul_f32_e32 v16, 0xbfb8aa3b, v168
	v_exp_f32_e32 v16, v16
	v_mul_f32_e32 v17, 0xbfb8aa3b, v169
	v_exp_f32_e32 v17, v17
	v_pk_mul_f32 v[14:15], v[176:177], v[14:15]
	v_pk_fma_f32 v[172:173], v[22:23], v[192:193], v[172:173]
	v_cvt_pk_bf16_f32 v14, v14, v15
	v_add_f32_e32 v15, 1.0, v16
	v_rcp_f32_e32 v16, v15
	v_add_f32_e32 v15, 1.0, v17
	v_rcp_f32_e32 v17, v15
	v_mul_f32_e32 v15, 0xbfb8aa3b, v172
	v_exp_f32_e32 v15, v15
	v_mul_f32_e32 v126, 0xbfb8aa3b, v173
	v_exp_f32_e32 v126, v126
	v_pk_fma_f32 v[174:175], v[24:25], v[112:113], v[174:175]
	v_add_f32_e32 v15, 1.0, v15
	v_pk_mul_f32 v[16:17], v[168:169], v[16:17]
	v_rcp_f32_e32 v168, v15
	v_add_f32_e32 v15, 1.0, v126
	v_mul_f32_e32 v126, 0xbfb8aa3b, v174
	v_exp_f32_e32 v126, v126
	v_mul_f32_e32 v169, 0xbfb8aa3b, v175
	v_exp_f32_e32 v177, v169
	v_rcp_f32_e32 v169, v15
	v_add_f32_e32 v15, 1.0, v126
	v_rcp_f32_e32 v176, v15
	v_add_f32_e32 v15, 1.0, v177
	s_waitcnt vmcnt(0)
	v_pk_fma_f32 v[98:99], v[18:19], v[194:195], v[98:99]
	v_rcp_f32_e32 v177, v15
	v_cvt_pk_bf16_f32 v15, v16, v17
	v_pk_mul_f32 v[16:17], v[172:173], v[168:169]
	v_pk_fma_f32 v[182:183], v[20:21], v[196:197], v[182:183]
	v_cvt_pk_bf16_f32 v16, v16, v17
	v_mul_f32_e32 v17, 0xbfb8aa3b, v98
	v_exp_f32_e32 v126, v17
	v_mul_f32_e32 v17, 0xbfb8aa3b, v99
	v_exp_f32_e32 v172, v17
	v_pk_mul_f32 v[168:169], v[174:175], v[176:177]
	v_add_f32_e32 v126, 1.0, v126
	v_cvt_pk_bf16_f32 v17, v168, v169
	v_mul_f32_e32 v169, 0xbfb8aa3b, v182
	v_rcp_f32_e32 v168, v126
	v_add_f32_e32 v126, 1.0, v172
	v_exp_f32_e32 v172, v169
	v_mul_f32_e32 v169, 0xbfb8aa3b, v183
	v_exp_f32_e32 v173, v169
	v_rcp_f32_e32 v169, v126
	v_add_f32_e32 v126, 1.0, v172
	v_rcp_f32_e32 v172, v126
	v_add_f32_e32 v126, 1.0, v173
	v_rcp_f32_e32 v173, v126
	v_pk_mul_f32 v[98:99], v[98:99], v[168:169]
	v_pk_fma_f32 v[100:101], v[10:11], v[198:199], v[100:101]
	v_pk_mul_f32 v[98:99], v[98:99], s[38:39] op_sel_hi:[1,0]
	v_pk_mul_f32 v[168:169], v[182:183], v[172:173]
	v_cvt_pk_bf16_f32 v98, v98, v99
	v_mul_f32_e32 v99, 0xbfb8aa3b, v100
	v_exp_f32_e32 v126, v99
	v_mul_f32_e32 v99, 0xbfb8aa3b, v101
	v_exp_f32_e32 v172, v99
	v_pk_fma_f32 v[188:189], v[12:13], v[200:201], v[188:189]
	v_pk_mul_f32 v[168:169], v[168:169], s[38:39] op_sel_hi:[1,0]
	v_add_f32_e32 v126, 1.0, v126
	v_cvt_pk_bf16_f32 v99, v168, v169
	v_mul_f32_e32 v169, 0xbfb8aa3b, v188
	v_rcp_f32_e32 v168, v126
	v_add_f32_e32 v126, 1.0, v172
	v_exp_f32_e32 v172, v169
	v_mul_f32_e32 v169, 0xbfb8aa3b, v189
	v_exp_f32_e32 v173, v169
	v_rcp_f32_e32 v169, v126
	v_add_f32_e32 v126, 1.0, v172
	v_rcp_f32_e32 v172, v126
	v_add_f32_e32 v126, 1.0, v173
	v_rcp_f32_e32 v173, v126
	v_pk_mul_f32 v[100:101], v[100:101], v[168:169]
	v_pk_fma_f32 v[26:27], v[26:27], v[114:115], v[58:59]
	v_pk_mul_f32 v[100:101], v[100:101], s[38:39] op_sel_hi:[1,0]
	v_pk_mul_f32 v[168:169], v[188:189], v[172:173]
	v_cvt_pk_bf16_f32 v100, v100, v101
	v_pk_mul_f32 v[168:169], v[168:169], s[38:39] op_sel_hi:[1,0]
	v_pk_fma_f32 v[26:27], v[50:51], v[170:171], v[26:27]
	v_cvt_pk_bf16_f32 v101, v168, v169
	v_lshl_add_u64 v[168:169], s[26:27], 0, v[152:153]
	v_add_co_u32_e32 v168, vcc, s68, v168
	v_pk_fma_f32 v[26:27], v[82:83], v[192:193], v[26:27]
	s_nop 0
	v_addc_co_u32_e32 v169, vcc, 0, v169, vcc
	global_store_dwordx4 v[168:169], v[14:17], off
	v_pk_fma_f32 v[40:41], v[44:45], v[40:41], v[64:65]
	v_pk_fma_f32 v[28:29], v[28:29], v[116:117], v[60:61]
	v_pk_fma_f32 v[16:17], v[32:33], v[104:105], v[92:93]
	v_pk_fma_f32 v[14:15], v[30:31], v[102:103], v[90:91]
	v_pk_fma_f32 v[16:17], v[88:89], v[106:107], v[16:17]
	v_pk_fma_f32 v[32:33], v[68:69], v[38:39], v[96:97]
	v_pk_fma_f32 v[38:39], v[42:43], v[120:121], v[62:63]
	v_pk_fma_f32 v[14:15], v[86:87], v[154:155], v[14:15]
	v_pk_fma_f32 v[16:17], v[72:73], v[110:111], v[16:17]
	v_lshlrev_b32_e32 v42, 16, v6
	v_and_b32_e32 v43, 0xffff0000, v6
	v_lshlrev_b32_e32 v6, 16, v7
	v_and_b32_e32 v7, 0xffff0000, v7
	v_pk_fma_f32 v[30:31], v[66:67], v[118:119], v[94:95]
	v_pk_fma_f32 v[32:33], v[80:81], v[180:181], v[32:33]
	v_pk_fma_f32 v[14:15], v[70:71], v[190:191], v[14:15]
	v_pk_fma_f32 v[6:7], v[36:37], v[6:7], v[16:17]
	v_lshlrev_b32_e32 v16, 16, v8
	v_and_b32_e32 v17, 0xffff0000, v8
	v_pk_fma_f32 v[30:31], v[78:79], v[178:179], v[30:31]
	v_pk_fma_f32 v[32:33], v[76:77], v[196:197], v[32:33]
	v_pk_fma_f32 v[14:15], v[34:35], v[42:43], v[14:15]
	v_pk_fma_f32 v[16:17], v[22:23], v[16:17], v[26:27]
	v_lshlrev_b32_e32 v22, 16, v2
	v_and_b32_e32 v23, 0xffff0000, v2
	v_lshlrev_b32_e32 v2, 16, v3
	v_and_b32_e32 v3, 0xffff0000, v3
	v_pk_fma_f32 v[30:31], v[74:75], v[194:195], v[30:31]
	v_pk_fma_f32 v[20:21], v[20:21], v[2:3], v[32:33]
	v_lshlrev_b32_e32 v2, 16, v4
	v_and_b32_e32 v3, 0xffff0000, v4
	v_mul_f32_e32 v4, 0xbfb8aa3b, v14
	v_pk_fma_f32 v[18:19], v[18:19], v[22:23], v[30:31]
	v_exp_f32_e32 v22, v4
	v_mul_f32_e32 v4, 0xbfb8aa3b, v15
	v_exp_f32_e32 v23, v4
	v_pk_fma_f32 v[40:41], v[48:49], v[186:187], v[40:41]
	v_lshlrev_b32_e32 v4, 16, v5
	v_pk_fma_f32 v[40:41], v[56:57], v[200:201], v[40:41]
	v_add_f32_e32 v22, 1.0, v22
	v_add_f32_e32 v23, 1.0, v23
	v_and_b32_e32 v5, 0xffff0000, v5
	v_rcp_f32_e32 v22, v22
	v_rcp_f32_e32 v23, v23
	v_pk_fma_f32 v[12:13], v[12:13], v[4:5], v[40:41]
	v_mul_f32_e32 v4, 0xbfb8aa3b, v6
	v_exp_f32_e32 v4, v4
	v_mul_f32_e32 v5, 0xbfb8aa3b, v7
	v_pk_fma_f32 v[38:39], v[46:47], v[184:185], v[38:39]
	v_exp_f32_e32 v5, v5
	v_pk_fma_f32 v[38:39], v[54:55], v[198:199], v[38:39]
	v_pk_fma_f32 v[28:29], v[52:53], v[108:109], v[28:29]
	v_pk_fma_f32 v[10:11], v[10:11], v[2:3], v[38:39]
	v_pk_mul_f32 v[2:3], v[14:15], v[22:23]
	v_mul_f32_e32 v14, 0xbfb8aa3b, v17
	v_cvt_pk_bf16_f32 v2, v2, v3
	v_add_f32_e32 v3, 1.0, v4
	v_rcp_f32_e32 v4, v3
	v_add_f32_e32 v3, 1.0, v5
	v_rcp_f32_e32 v5, v3
	v_mul_f32_e32 v3, 0xbfb8aa3b, v16
	v_exp_f32_e32 v3, v3
	v_exp_f32_e32 v14, v14
	v_pk_fma_f32 v[28:29], v[84:85], v[112:113], v[28:29]
	v_lshlrev_b32_e32 v8, 16, v9
	v_and_b32_e32 v9, 0xffff0000, v9
	v_pk_fma_f32 v[8:9], v[24:25], v[8:9], v[28:29]
	v_pk_mul_f32 v[4:5], v[6:7], v[4:5]
	v_add_f32_e32 v3, 1.0, v3
	v_mul_f32_e32 v7, 0xbfb8aa3b, v8
	v_rcp_f32_e32 v6, v3
	v_add_f32_e32 v3, 1.0, v14
	v_exp_f32_e32 v14, v7
	v_mul_f32_e32 v7, 0xbfb8aa3b, v9
	v_exp_f32_e32 v15, v7
	v_rcp_f32_e32 v7, v3
	v_add_f32_e32 v3, 1.0, v14
	v_rcp_f32_e32 v14, v3
	v_add_f32_e32 v3, 1.0, v15
	v_rcp_f32_e32 v15, v3
	v_cvt_pk_bf16_f32 v3, v4, v5
	v_pk_mul_f32 v[4:5], v[16:17], v[6:7]
	ds_write_b128 v160, v[98:101]
	v_cvt_pk_bf16_f32 v4, v4, v5
	v_mul_f32_e32 v5, 0xbfb8aa3b, v18
	v_pk_mul_f32 v[6:7], v[8:9], v[14:15]
	v_exp_f32_e32 v8, v5
	v_mul_f32_e32 v5, 0xbfb8aa3b, v19
	v_exp_f32_e32 v9, v5
	v_cvt_pk_bf16_f32 v5, v6, v7
	v_add_f32_e32 v6, 1.0, v8
	v_rcp_f32_e32 v6, v6
	v_add_f32_e32 v7, 1.0, v9
	v_mul_f32_e32 v8, 0xbfb8aa3b, v20
	v_mul_f32_e32 v9, 0xbfb8aa3b, v21
	v_rcp_f32_e32 v7, v7
	v_exp_f32_e32 v8, v8
	v_exp_f32_e32 v9, v9
	global_store_dwordx4 v[168:169], v[2:5], off offset:1024
	v_pk_mul_f32 v[6:7], v[18:19], v[6:7]
	v_add_f32_e32 v8, 1.0, v8
	v_add_f32_e32 v9, 1.0, v9
	v_pk_mul_f32 v[6:7], v[6:7], s[38:39] op_sel_hi:[1,0]
	v_rcp_f32_e32 v8, v8
	v_rcp_f32_e32 v9, v9
	v_cvt_pk_bf16_f32 v6, v6, v7
	v_mul_f32_e32 v7, 0xbfb8aa3b, v10
	v_exp_f32_e32 v14, v7
	v_mul_f32_e32 v7, 0xbfb8aa3b, v11
	v_exp_f32_e32 v15, v7
	v_pk_mul_f32 v[8:9], v[20:21], v[8:9]
	v_lshl_add_u64 v[152:153], v[152:153], 0, s[42:43]
	v_pk_mul_f32 v[8:9], v[8:9], s[38:39] op_sel_hi:[1,0]
	s_nop 0
	v_cvt_pk_bf16_f32 v7, v8, v9
	v_add_f32_e32 v8, 1.0, v14
	v_add_f32_e32 v9, 1.0, v15
	v_mul_f32_e32 v14, 0xbfb8aa3b, v12
	v_mul_f32_e32 v15, 0xbfb8aa3b, v13
	v_exp_f32_e32 v14, v14
	v_exp_f32_e32 v15, v15
	v_rcp_f32_e32 v8, v8
	v_rcp_f32_e32 v9, v9
	v_add_f32_e32 v14, 1.0, v14
	v_add_f32_e32 v15, 1.0, v15
	v_rcp_f32_e32 v14, v14
	v_rcp_f32_e32 v15, v15
	v_pk_mul_f32 v[8:9], v[10:11], v[8:9]
	v_pk_mul_f32 v[10:11], v[12:13], v[14:15]
	v_pk_mul_f32 v[8:9], v[8:9], s[38:39] op_sel_hi:[1,0]
	v_pk_mul_f32 v[10:11], v[10:11], s[38:39] op_sel_hi:[1,0]
	v_cvt_pk_bf16_f32 v8, v8, v9
	v_cvt_pk_bf16_f32 v9, v10, v11
	ds_write_b128 v161, v[6:9]
	s_waitcnt lgkmcnt(0)
	s_barrier
	v_add_u32_e32 v230, s39, v157
	v_add_u32_e32 v230, 61, v230
	v_mov_b32_e32 v231, 0
	v_lshl_add_u64 v[230:231], s[20:21], 0, v[230:231]
	v_lshlrev_b64 v[230:231], 10, v[230:231]
	v_lshl_or_b32 v230, v124, 1, v230
	v_lshl_add_u64 v[232:233], s[28:29], 0, v[230:231]
	v_lshl_add_u64 v[234:235], s[30:31], 0, v[230:231]
	global_load_dwordx4 v[202:205], v[232:233], off
	global_load_dwordx4 v[206:209], v[234:235], off
	global_load_dwordx4 v[210:213], v[232:233], off offset:1024
	global_load_dwordx4 v[214:217], v[234:235], off offset:1024
	global_load_dwordx4 v[218:221], v[232:233], off offset:2048
	global_load_dwordx4 v[222:225], v[234:235], off offset:2048
	global_load_dwordx4 v[226:229], v[232:233], off offset:3072
	global_load_dwordx4 v[202:205], v[234:235], off offset:3072
	s_mov_b64 s[100:101], 0x1000
	v_lshl_add_u64 v[232:233], v[232:233], 0, s[100:101]
	v_lshl_add_u64 v[234:235], v[234:235], 0, s[100:101]
	global_load_dwordx4 v[206:209], v[232:233], off
	global_load_dwordx4 v[210:213], v[234:235], off
	ds_read_u16 v6, v162
	ds_read_u16 v2, v162 offset:272
	ds_read_u16 v20, v162 offset:544
	ds_read_u16 v21, v162 offset:816
	ds_read_u16 v22, v162 offset:1088
	ds_read_u16 v23, v162 offset:1360
	ds_read_u16 v24, v162 offset:1632
	ds_read_u16 v25, v162 offset:1904
	s_waitcnt lgkmcnt(6)
	v_lshlrev_b32_e32 v19, 16, v2
	ds_read_b128 v[2:5], v125 offset:34816
	v_lshlrev_b32_e32 v18, 16, v6
	ds_read_b128 v[6:9], v125 offset:34832
	ds_read_b128 v[10:13], v125 offset:34848
	ds_read_b128 v[14:17], v125 offset:34864
	s_waitcnt lgkmcnt(8)
	v_lshlrev_b32_e32 v21, 16, v21
	v_lshlrev_b32_e32 v20, 16, v20
	s_waitcnt lgkmcnt(3)
	v_pk_mul_f32 v[2:3], v[2:3], v[18:19]
	v_pk_mul_f32 v[4:5], v[4:5], v[20:21]
	v_cvt_pk_bf16_f32 v2, v2, v3
	ds_read_u16 v3, v162 offset:17408
	ds_read_u16 v18, v162 offset:17680
	ds_read_u16 v19, v162 offset:17952
	ds_read_u16 v26, v162 offset:18224
	ds_read_u16 v27, v162 offset:18496
	ds_read_u16 v28, v162 offset:18768
	ds_read_u16 v29, v162 offset:19040
	ds_read_u16 v30, v162 offset:19312
	s_waitcnt lgkmcnt(6)
	v_lshl_or_b32 v18, v18, 16, v3
	v_cvt_pk_bf16_f32 v3, v4, v5
	v_lshlrev_b32_e32 v5, 16, v23
	v_lshlrev_b32_e32 v4, 16, v22
	v_pk_mul_f32 v[4:5], v[6:7], v[4:5]
	v_lshlrev_b32_e32 v7, 16, v25
	v_lshlrev_b32_e32 v6, 16, v24
	v_pk_mul_f32 v[6:7], v[8:9], v[6:7]
	v_cvt_pk_bf16_f32 v4, v4, v5
	v_cvt_pk_bf16_f32 v5, v6, v7
	ds_read_u16 v6, v162 offset:2176
	ds_read_u16 v7, v162 offset:2448
	ds_read_u16 v8, v162 offset:2720
	ds_read_u16 v9, v162 offset:2992
	ds_read_u16 v22, v162 offset:3264
	ds_read_u16 v23, v162 offset:3536
	ds_read_u16 v24, v162 offset:3808
	ds_read_u16 v25, v162 offset:4080
	s_waitcnt lgkmcnt(6)
	v_lshlrev_b32_e32 v7, 16, v7
	v_lshlrev_b32_e32 v6, 16, v6
	v_pk_mul_f32 v[6:7], v[10:11], v[6:7]
	s_waitcnt lgkmcnt(4)
	v_lshlrev_b32_e32 v9, 16, v9
	v_lshlrev_b32_e32 v8, 16, v8
	v_lshl_or_b32 v19, v26, 16, v19
	v_lshl_or_b32 v20, v28, 16, v27
	v_lshl_or_b32 v21, v30, 16, v29
	v_cvt_pk_bf16_f32 v6, v6, v7
	ds_read_u16 v7, v162 offset:19584
	ds_read_u16 v10, v162 offset:19856
	ds_read_u16 v11, v162 offset:20128
	ds_read_u16 v26, v162 offset:20400
	ds_read_u16 v27, v162 offset:20672
	ds_read_u16 v28, v162 offset:20944
	ds_read_u16 v29, v162 offset:21216
	ds_read_u16 v30, v162 offset:21488
	v_pk_mul_f32 v[8:9], v[12:13], v[8:9]
	s_waitcnt lgkmcnt(6)
	v_lshl_or_b32 v10, v10, 16, v7
	v_cvt_pk_bf16_f32 v7, v8, v9
	v_lshlrev_b32_e32 v9, 16, v23
	v_lshlrev_b32_e32 v8, 16, v22
	v_pk_mul_f32 v[8:9], v[14:15], v[8:9]
	v_lshlrev_b32_e32 v15, 16, v25
	v_lshlrev_b32_e32 v14, 16, v24
	v_pk_mul_f32 v[14:15], v[16:17], v[14:15]
	v_cvt_pk_bf16_f32 v8, v8, v9
	v_cvt_pk_bf16_f32 v9, v14, v15
	v_lshl_add_u64 v[14:15], s[26:27], 0, v[144:145]
	v_add_co_u32_e32 v16, vcc, s69, v14
	s_add_i32 s39, s39, 64
	s_nop 0
	v_addc_co_u32_e32 v17, vcc, 0, v15, vcc
	s_add_u32 s50, s50, 8
	global_store_dwordx4 v[16:17], v[2:5], off
	global_store_dwordx4 v[16:17], v[6:9], off offset:16
	s_addc_u32 s51, s51, 0
	v_add_co_u32_e32 v2, vcc, s70, v14
	v_lshl_add_u64 v[144:145], v[144:145], 0, s[40:41]
	s_nop 0
	v_addc_co_u32_e32 v3, vcc, 0, v15, vcc
	s_cmpk_eq_i32 s39, 0x100
	s_waitcnt lgkmcnt(4)
	v_lshl_or_b32 v11, v26, 16, v11
	s_waitcnt lgkmcnt(2)
	v_lshl_or_b32 v12, v28, 16, v27
	s_waitcnt lgkmcnt(0)
	v_lshl_or_b32 v13, v30, 16, v29
	global_store_dwordx4 v[2:3], v[18:21], off
	global_store_dwordx4 v[2:3], v[10:13], off offset:16
	s_barrier
	s_cbranch_scc1 .LBB0_863
